# cost-weighted spacing: each PV MFMA leads half of next group's softmax VALU (exp block / pack+sum block)
# baseline (speedup 1.0000x reference)
.LBB0_381:
	s_barrier
	s_mulk_i32 s3, 0x2400
	v_add3_u32 v190, v143, s3, v142
	v_add_u32_e32 v191, 0x6800, v190
	v_add_u32_e32 v192, 0x7a00, v190
	ds_read2_b64 v[194:197], v191 offset1:2
	ds_read2_b64 v[198:201], v192 offset1:2
	ds_read2_b64 v[202:205], v191 offset0:4 offset1:6
	ds_read2_b64 v[206:209], v192 offset0:4 offset1:6
	ds_read2_b64 v[210:213], v191 offset0:8 offset1:10
	ds_read2_b64 v[214:217], v192 offset0:8 offset1:10
	ds_read2_b64 v[218:221], v191 offset0:12 offset1:14
	ds_read2_b64 v[222:225], v192 offset0:12 offset1:14
	v_exp_f32_e32 v32, v32
	v_exp_f32_e32 v33, v33
	v_exp_f32_e32 v34, v34
	v_exp_f32_e32 v35, v35
	v_exp_f32_e32 v36, v36
	v_exp_f32_e32 v37, v37
	v_exp_f32_e32 v38, v38
	v_exp_f32_e32 v39, v39
	v_cvt_pk_bf16_f32 v160, v32, v33
	v_cvt_pk_bf16_f32 v161, v34, v35
	v_cvt_pk_bf16_f32 v162, v36, v37
	v_cvt_pk_bf16_f32 v163, v38, v39
	v_add_f32_e32 v168, v32, v33
	v_add_f32_e32 v169, v34, v35
	v_add_f32_e32 v168, v168, v36
	v_add_f32_e32 v169, v169, v37
	v_add_f32_e32 v168, v168, v38
	v_add_f32_e32 v169, v169, v39
	s_waitcnt lgkmcnt(6)
	v_mfma_f32_32x32x16_bf16 v[16:31], v[194:197], v[160:163], v[16:31]
	v_exp_f32_e32 v40, v40
	v_exp_f32_e32 v41, v41
	v_exp_f32_e32 v42, v42
	v_exp_f32_e32 v43, v43
	v_exp_f32_e32 v44, v44
	v_exp_f32_e32 v45, v45
	v_exp_f32_e32 v46, v46
	v_exp_f32_e32 v47, v47
	v_mfma_f32_32x32x16_bf16 v[0:15], v[198:201], v[160:163], v[0:15]
	v_cvt_pk_bf16_f32 v164, v40, v41
	v_cvt_pk_bf16_f32 v165, v42, v43
	v_cvt_pk_bf16_f32 v166, v44, v45
	v_cvt_pk_bf16_f32 v167, v46, v47
	v_add_f32_e32 v168, v168, v40
	v_add_f32_e32 v169, v169, v41
	v_add_f32_e32 v168, v168, v42
	v_add_f32_e32 v169, v169, v43
	v_add_f32_e32 v168, v168, v44
	v_add_f32_e32 v169, v169, v45
	v_add_f32_e32 v168, v168, v46
	v_add_f32_e32 v169, v169, v47
	s_waitcnt lgkmcnt(4)
	v_mfma_f32_32x32x16_bf16 v[16:31], v[202:205], v[164:167], v[16:31]
	v_exp_f32_e32 v48, v48
	v_exp_f32_e32 v49, v49
	v_exp_f32_e32 v50, v50
	v_exp_f32_e32 v51, v51
	v_exp_f32_e32 v52, v52
	v_exp_f32_e32 v53, v53
	v_exp_f32_e32 v54, v54
	v_exp_f32_e32 v55, v55
	v_mfma_f32_32x32x16_bf16 v[0:15], v[206:209], v[164:167], v[0:15]
	v_cvt_pk_bf16_f32 v160, v48, v49
	v_cvt_pk_bf16_f32 v161, v50, v51
	v_cvt_pk_bf16_f32 v162, v52, v53
	v_cvt_pk_bf16_f32 v163, v54, v55
	v_add_f32_e32 v168, v168, v48
	v_add_f32_e32 v169, v169, v49
	v_add_f32_e32 v168, v168, v50
	v_add_f32_e32 v169, v169, v51
	v_add_f32_e32 v168, v168, v52
	v_add_f32_e32 v169, v169, v53
	v_add_f32_e32 v168, v168, v54
	v_add_f32_e32 v169, v169, v55
	s_waitcnt lgkmcnt(2)
	v_mfma_f32_32x32x16_bf16 v[16:31], v[210:213], v[160:163], v[16:31]
	v_exp_f32_e32 v56, v56
	v_exp_f32_e32 v57, v57
	v_exp_f32_e32 v58, v58
	v_exp_f32_e32 v59, v59
	v_exp_f32_e32 v60, v60
	v_exp_f32_e32 v61, v61
	v_exp_f32_e32 v62, v62
	v_exp_f32_e32 v63, v63
	v_mfma_f32_32x32x16_bf16 v[0:15], v[214:217], v[160:163], v[0:15]
	v_cvt_pk_bf16_f32 v164, v56, v57
	v_cvt_pk_bf16_f32 v165, v58, v59
	v_cvt_pk_bf16_f32 v166, v60, v61
	v_cvt_pk_bf16_f32 v167, v62, v63
	v_add_f32_e32 v168, v168, v56
	v_add_f32_e32 v169, v169, v57
	v_add_f32_e32 v168, v168, v58
	v_add_f32_e32 v169, v169, v59
	v_add_f32_e32 v168, v168, v60
	v_add_f32_e32 v169, v169, v61
	v_add_f32_e32 v168, v168, v62
	v_add_f32_e32 v169, v169, v63
	v_add_f32_e32 v168, v168, v169
	v_add_f32_e32 v119, v119, v168
	s_add_i32 s1, s1, 64
	s_cmpk_lg_i32 s1, 0x11c0
	s_waitcnt lgkmcnt(0)
	s_barrier
	v_mfma_f32_32x32x16_bf16 v[16:31], v[218:221], v[164:167], v[16:31]
	v_mfma_f32_32x32x16_bf16 v[0:15], v[222:225], v[164:167], v[0:15]
	s_cbranch_scc0 .LBB0_383
	s_mov_b32 s3, s2
	s_branch .LBB0_377
